# v90 + norm phases: per-row g/shift/scale vectors read from an LDS copy loaded once per phase (12 ds_read_b128 per row instead of 12 L2 loads)
# speedup vs baseline: 1.2221x; 1.0109x over previous
.LBB0_439:
	s_cmp_gt_i32 s47, 3
	s_mov_b64 s[2:3], -1
	s_cbranch_scc0 .LBB0_482
	v_ashrrev_i32_e32 v0, 6, v166
	v_readlane_b32 s2, v252, 17
	s_nop 1
	v_add_u32_e32 v66, s2, v0
	v_cmp_gt_i32_e32 vcc, s4, v66
	s_and_saveexec_b64 s[2:3], vcc
	s_cbranch_execz .LBB0_481
	v_and_b32_e32 v3, 64, v220
	v_add_u32_e32 v3, 64, v3
	v_xor_b32_e32 v5, 32, v220
	v_cmp_lt_i32_e32 vcc, v5, v3
	s_load_dword s12, s[96:97], 0x0
	v_lshlrev_b32_e32 v0, 2, v166
	v_cndmask_b32_e32 v5, v220, v5, vcc
	v_lshlrev_b32_e32 v108, 2, v5
	v_xor_b32_e32 v5, 16, v220
	v_cmp_lt_i32_e32 vcc, v5, v3
	v_and_b32_e32 v2, 0xfc, v0
	s_waitcnt lgkmcnt(0)
	s_lshl_b32 s5, s12, 3
	v_cndmask_b32_e32 v5, v220, v5, vcc
	v_lshlrev_b32_e32 v109, 2, v5
	v_xor_b32_e32 v5, 8, v220
	v_cmp_lt_i32_e32 vcc, v5, v3
	s_add_u32 s8, s44, 0x32000
	v_or_b32_e32 v4, 0x100, v2
	v_cndmask_b32_e32 v5, v220, v5, vcc
	s_addc_u32 s9, s45, 0
	v_readlane_b32 s6, v254, 57
	v_lshlrev_b32_e32 v6, 2, v4
	v_mov_b32_e32 v7, v1
	v_lshlrev_b32_e32 v110, 2, v5
	v_xor_b32_e32 v5, 4, v220
	v_readlane_b32 s7, v254, 58
	s_lshl_b32 s6, s6, 10
	v_lshl_add_u64 v[70:71], s[8:9], 0, v[6:7]
	v_or_b32_e32 v6, 0x200, v2
	v_cmp_lt_i32_e32 vcc, v5, v3
	s_ashr_i32 s7, s6, 31
	v_lshlrev_b32_e32 v8, 2, v6
	v_mov_b32_e32 v9, v1
	v_cndmask_b32_e32 v5, v220, v5, vcc
	s_lshl_b64 s[6:7], s[6:7], 2
	v_lshl_add_u64 v[72:73], s[8:9], 0, v[8:9]
	v_or_b32_e32 v8, 0x300, v2
	v_lshlrev_b32_e32 v111, 2, v5
	v_xor_b32_e32 v5, 2, v220
	s_add_u32 s10, s86, s6
	v_lshlrev_b32_e32 v0, 2, v2
	v_lshlrev_b32_e32 v10, 2, v8
	v_mov_b32_e32 v11, v1
	v_cmp_lt_i32_e32 vcc, v5, v3
	s_addc_u32 s11, s87, s7
	s_add_i32 s6, s4, -1
	v_lshl_add_u64 v[68:69], s[8:9], 0, v[0:1]
	v_lshl_add_u64 v[74:75], s[8:9], 0, v[10:11]
	v_cndmask_b32_e32 v5, v220, v5, vcc
	v_readlane_b32 s8, v253, 39
	s_add_u32 s22, s44, 0x3000
	v_lshlrev_b32_e32 v112, 2, v5
	v_xor_b32_e32 v5, 1, v220
	v_lshl_add_u64 v[76:77], s[10:11], 0, v[0:1]
	v_lshl_add_u64 v[78:79], s[54:55], 0, v[0:1]
	v_lshlrev_b32_e32 v0, 1, v2
	v_readlane_b32 s9, v253, 40
	v_ashrrev_i32_e32 v67, 31, v66
	s_addc_u32 s23, s45, 0
	s_lshl_b32 s24, s12, 5
	v_cmp_lt_i32_e32 vcc, v5, v3
	v_lshl_add_u64 v[80:81], s[8:9], 0, v[0:1]
	v_lshlrev_b64 v[10:11], 11, v[66:67]
	v_and_b32_e32 v0, 63, v166
	v_cndmask_b32_e32 v3, v220, v5, vcc
	v_lshl_or_b32 v10, v0, 3, v10
	s_ashr_i32 s25, s24, 31
	v_lshlrev_b32_e32 v113, 2, v3
	v_lshl_add_u64 v[82:83], s[8:9], 0, v[10:11]
	s_lshl_b64 s[30:31], s[24:25], 11
	s_lshl_b32 s7, s12, 4
	s_mul_i32 s8, s12, 24
	v_readlane_b32 s12, v254, 54
	s_mov_b64 s[34:35], 0
	v_lshlrev_b32_e32 v84, 2, v2
	v_lshlrev_b32_e32 v86, 2, v4
	v_lshlrev_b32_e32 v88, 2, v6
	v_lshlrev_b32_e32 v90, 2, v8
	v_and_b32_e32 v223, 63, v166
	v_lshlrev_b32_e32 v223, 4, v223
	v_add_u32_e32 v242, 0x12000, v223
	v_lshlrev_b32_e32 v50, 4, v166
	s_mov_b64 s[98:99], s[22:23]
	global_load_dwordx4 v[10:13], v50, s[98:99]
	s_add_u32 s98, s98, 0x6000
	s_addc_u32 s99, s99, 0
	global_load_dwordx4 v[14:17], v50, s[98:99]
	s_add_u32 s98, s98, 0x6000
	s_addc_u32 s99, s99, 0
	global_load_dwordx4 v[18:21], v50, s[98:99]
	s_add_u32 s98, s98, 0x6000
	s_addc_u32 s99, s99, 0
	global_load_dwordx4 v[22:25], v50, s[98:99]
	s_add_u32 s98, s98, 0x6000
	s_addc_u32 s99, s99, 0
	global_load_dwordx4 v[26:29], v50, s[98:99]
	s_add_u32 s98, s98, 0x6000
	s_addc_u32 s99, s99, 0
	global_load_dwordx4 v[30:33], v50, s[98:99]
	s_add_u32 s98, s98, 0x6000
	s_addc_u32 s99, s99, 0
	global_load_dwordx4 v[34:37], v50, s[98:99]
	s_add_u32 s98, s98, 0x6000
	s_addc_u32 s99, s99, 0
	global_load_dwordx4 v[38:41], v50, s[98:99]
	s_add_u32 s98, s98, 0x6000
	s_addc_u32 s99, s99, 0
	global_load_dwordx4 v[42:45], v50, s[98:99]
	s_add_u32 s98, s98, 0x6000
	s_addc_u32 s99, s99, 0
	v_lshrrev_b32_e32 v54, 6, v166
	v_lshlrev_b32_e32 v54, 10, v54
	v_mov_b32_e32 v55, 0
	v_lshl_add_u64 v[52:53], v[76:77], 0, v[54:55]
	v_add_u32_e32 v51, 0x12000, v50
	v_cmp_gt_u32_e32 vcc, 0x100, v166
	s_and_saveexec_b64 s[98:99], vcc
	global_load_dwordx4 v[46:49], v[52:53], off
	s_waitcnt vmcnt(0)
	ds_write_b128 v51, v[46:49]
	s_mov_b64 exec, s[98:99]
	ds_write_b128 v50, v[10:13]
	v_add_u32_e32 v50, 0x2000, v50
	ds_write_b128 v50, v[14:17]
	v_add_u32_e32 v50, 0x2000, v50
	ds_write_b128 v50, v[18:21]
	v_add_u32_e32 v50, 0x2000, v50
	ds_write_b128 v50, v[22:25]
	v_add_u32_e32 v50, 0x2000, v50
	ds_write_b128 v50, v[26:29]
	v_add_u32_e32 v50, 0x2000, v50
	ds_write_b128 v50, v[30:33]
	v_add_u32_e32 v50, 0x2000, v50
	ds_write_b128 v50, v[34:37]
	v_add_u32_e32 v50, 0x2000, v50
	ds_write_b128 v50, v[38:41]
	v_add_u32_e32 v50, 0x2000, v50
	ds_write_b128 v50, v[42:45]
	s_waitcnt lgkmcnt(0)
	s_barrier
	s_branch .LBB0_443

.LBB0_475:
	s_or_b64 exec, exec, s[36:37]
	s_waitcnt vmcnt(0)
	v_mul_f32_e32 v0, v63, v63
	v_mul_f32_e32 v67, v51, v51
	v_fmac_f32_e32 v0, v62, v62
	v_fmac_f32_e32 v67, v50, v50
	v_fmac_f32_e32 v0, v64, v64
	v_fmac_f32_e32 v67, v52, v52
	v_fmac_f32_e32 v0, v65, v65
	v_fmac_f32_e32 v67, v53, v53
	v_add_f32_e32 v0, v67, v0
	v_mul_f32_e32 v67, v47, v47
	v_fmac_f32_e32 v67, v46, v46
	v_fmac_f32_e32 v67, v48, v48
	v_fmac_f32_e32 v67, v49, v49
	v_add_f32_e32 v0, v67, v0
	v_mul_f32_e32 v67, v31, v31
	v_fmac_f32_e32 v67, v30, v30
	v_fmac_f32_e32 v67, v32, v32
	v_fmac_f32_e32 v67, v33, v33
	v_add_f32_e32 v0, v67, v0
	v_min_i32_e32 v67, 0x8000, v66
	v_ashrrev_i32_e32 v67, 12, v67
	v_lshl_add_u32 v222, v67, 13, v223
	v_mul_i32_i24_e32 v98, 0x1800, v67
	v_ashrrev_i32_e32 v99, 31, v98
	v_lshl_add_u64 v[100:101], v[98:99], 2, s[22:23]
	s_mov_b64 s[10:11], 0x1000
	v_lshl_add_u64 v[98:99], v[100:101], 0, s[10:11]
	v_mov_b32_e32 v85, v1
	v_lshl_add_u64 v[106:107], v[98:99], 0, v[84:85]
	ds_read_b128 v[102:105], v242
	ds_read_b128 v[114:117], v222 offset:4096
	v_lshl_add_u64 v[100:101], v[100:101], 0, v[84:85]
	ds_read_b128 v[118:121], v222
	v_mov_b32_e32 v87, v1
	v_mov_b32_e32 v89, v1
	v_mov_b32_e32 v91, v1
	ds_read_b128 v[168:171], v242 offset:1024
	v_lshl_add_u64 v[172:173], v[98:99], 0, v[86:87]
	ds_read_b128 v[172:175], v222 offset:5120
	ds_read_b128 v[176:179], v222 offset:1024
	ds_read_b128 v[180:183], v242 offset:2048
	v_lshl_add_u64 v[184:185], v[98:99], 0, v[88:89]
	ds_read_b128 v[184:187], v222 offset:6144
	ds_read_b128 v[188:191], v222 offset:2048
	ds_read_b128 v[192:195], v242 offset:3072
	v_lshl_add_u64 v[196:197], v[98:99], 0, v[90:91]
	ds_read_b128 v[196:199], v222 offset:7168
	ds_read_b128 v[200:203], v222 offset:3072
	ds_bpermute_b32 v67, v108, v0
	v_mov_b32_e32 v87, v1
	v_mov_b32_e32 v89, v1
	v_mov_b32_e32 v91, v1
	s_waitcnt lgkmcnt(0)
	v_add_f32_e32 v0, v0, v67
	ds_bpermute_b32 v67, v109, v0
	s_waitcnt lgkmcnt(0)
	v_add_f32_e32 v0, v0, v67
	ds_bpermute_b32 v67, v110, v0
	s_waitcnt lgkmcnt(0)
	v_add_f32_e32 v0, v0, v67
	ds_bpermute_b32 v67, v111, v0
	s_waitcnt lgkmcnt(0)
	v_add_f32_e32 v0, v0, v67
	ds_bpermute_b32 v67, v112, v0
	s_waitcnt lgkmcnt(0)
	v_add_f32_e32 v0, v0, v67
	ds_bpermute_b32 v67, v113, v0
	s_waitcnt lgkmcnt(0)
	v_add_f32_e32 v0, v0, v67
	v_fmamk_f32 v0, v0, 0x3a800000, v218
	v_cmp_gt_f32_e32 vcc, s13, v0
	v_mul_f32_e32 v67, 0x4b800000, v0
	s_nop 0
	v_cndmask_b32_e32 v0, v0, v67, vcc
	v_rsq_f32_e32 v0, v0
	s_nop 0
	v_mul_f32_e32 v67, 0x45800000, v0
	v_cndmask_b32_e32 v0, v0, v67, vcc
	v_pk_mul_f32 v[64:65], v[64:65], v[0:1] op_sel_hi:[1,0]
	v_pk_mul_f32 v[62:63], v[62:63], v[0:1] op_sel_hi:[1,0]
	v_pk_mul_f32 v[52:53], v[52:53], v[0:1] op_sel_hi:[1,0]
	v_pk_mul_f32 v[50:51], v[50:51], v[0:1] op_sel_hi:[1,0]
	v_pk_mul_f32 v[48:49], v[48:49], v[0:1] op_sel_hi:[1,0]
	v_pk_mul_f32 v[46:47], v[46:47], v[0:1] op_sel_hi:[1,0]
	v_pk_mul_f32 v[32:33], v[32:33], v[0:1] op_sel_hi:[1,0]
	v_pk_mul_f32 v[30:31], v[30:31], v[0:1] op_sel_hi:[1,0]
	v_cmp_gt_i32_e32 vcc, s4, v96
	s_waitcnt vmcnt(11) lgkmcnt(0)
	v_pk_mul_f32 v[62:63], v[102:103], v[62:63]
	v_pk_mul_f32 v[64:65], v[104:105], v[64:65]
	s_waitcnt vmcnt(10) lgkmcnt(0)
	v_pk_add_f32 v[102:103], v[116:117], 1.0 op_sel_hi:[1,0]
	v_pk_add_f32 v[104:105], v[114:115], 1.0 op_sel_hi:[1,0]
	s_waitcnt vmcnt(9) lgkmcnt(0)
	v_pk_fma_f32 v[64:65], v[102:103], v[64:65], v[120:121]
	v_pk_fma_f32 v[62:63], v[104:105], v[62:63], v[118:119]
	v_lshl_add_u64 v[102:103], v[98:99], 0, v[86:87]
	v_cvt_pk_bf16_f32 v62, v62, v63
	v_cvt_pk_bf16_f32 v63, v64, v65
	global_store_dwordx2 v[82:83], v[62:63], off
	s_waitcnt vmcnt(7) lgkmcnt(0)
	v_pk_mul_f32 v[50:51], v[168:169], v[50:51]
	v_pk_mul_f32 v[52:53], v[170:171], v[52:53]
	v_pk_add_f32 v[62:63], v[174:175], 1.0 op_sel_hi:[1, 0]
	v_pk_add_f32 v[64:65], v[172:173], 1.0 op_sel_hi:[1, 0]
	v_pk_fma_f32 v[52:53], v[62:63], v[52:53], v[178:179]
	v_pk_fma_f32 v[50:51], v[64:65], v[50:51], v[176:177]
	v_lshl_add_u64 v[62:63], v[98:99], 0, v[88:89]
	v_cvt_pk_bf16_f32 v50, v50, v51
	v_cvt_pk_bf16_f32 v51, v52, v53
	global_store_dwordx2 v[82:83], v[50:51], off offset:512
	s_waitcnt vmcnt(5) lgkmcnt(0)
	v_pk_mul_f32 v[46:47], v[180:181], v[46:47]
	v_pk_mul_f32 v[48:49], v[182:183], v[48:49]
	v_pk_add_f32 v[50:51], v[186:187], 1.0 op_sel_hi:[1, 0]
	v_pk_add_f32 v[52:53], v[184:185], 1.0 op_sel_hi:[1, 0]
	v_pk_fma_f32 v[48:49], v[50:51], v[48:49], v[190:191]
	v_pk_fma_f32 v[46:47], v[52:53], v[46:47], v[188:189]
	v_lshl_add_u64 v[50:51], v[98:99], 0, v[90:91]
	v_cvt_pk_bf16_f32 v46, v46, v47
	v_cvt_pk_bf16_f32 v47, v48, v49
	global_store_dwordx2 v[82:83], v[46:47], off offset:1024
	s_waitcnt vmcnt(3) lgkmcnt(0)
	v_pk_mul_f32 v[30:31], v[30:31], v[192:193]
	v_pk_mul_f32 v[32:33], v[32:33], v[194:195]
	v_pk_add_f32 v[46:47], v[198:199], 1.0 op_sel_hi:[1, 0]
	v_pk_add_f32 v[48:49], v[196:197], 1.0 op_sel_hi:[1, 0]
	v_pk_fma_f32 v[32:33], v[32:33], v[46:47], v[202:203]
	v_pk_fma_f32 v[30:31], v[30:31], v[48:49], v[200:201]
	s_nop 0
	v_cvt_pk_bf16_f32 v30, v30, v31
	v_cvt_pk_bf16_f32 v31, v32, v33
	global_store_dwordx2 v[82:83], v[30:31], off offset:1536
	s_and_saveexec_b64 s[36:37], vcc
	s_cbranch_execz .LBB0_478
	v_mul_f32_e32 v0, v59, v59
	v_mul_f32_e32 v30, v43, v43
	v_fmac_f32_e32 v0, v58, v58
	v_fmac_f32_e32 v30, v42, v42
	v_fmac_f32_e32 v0, v60, v60
	v_fmac_f32_e32 v30, v44, v44
	v_fmac_f32_e32 v0, v61, v61
	v_fmac_f32_e32 v30, v45, v45
	v_add_f32_e32 v0, v30, v0
	v_mul_f32_e32 v30, v39, v39
	v_fmac_f32_e32 v30, v38, v38
	v_fmac_f32_e32 v30, v40, v40
	v_fmac_f32_e32 v30, v41, v41
	v_add_f32_e32 v0, v30, v0
	v_mul_f32_e32 v30, v35, v35
	v_fmac_f32_e32 v30, v34, v34
	v_fmac_f32_e32 v30, v36, v36
	v_fmac_f32_e32 v30, v37, v37
	v_add_f32_e32 v0, v30, v0
	ds_bpermute_b32 v46, v108, v0
	v_min_i32_e32 v30, 0x8000, v96
	v_ashrrev_i32_e32 v30, 12, v30
	v_lshl_add_u32 v222, v30, 13, v223
	v_mul_i32_i24_e32 v30, 0x1800, v30
	v_ashrrev_i32_e32 v31, 31, v30
	s_waitcnt lgkmcnt(0)
	v_add_f32_e32 v0, v0, v46
	ds_bpermute_b32 v46, v109, v0
	v_lshl_add_u64 v[32:33], v[30:31], 2, s[22:23]
	v_lshl_add_u64 v[30:31], v[32:33], 0, s[10:11]
	v_lshl_add_u64 v[52:53], v[30:31], 0, v[84:85]
	v_ashrrev_i32_e32 v97, 31, v96
	s_waitcnt lgkmcnt(0)
	v_add_f32_e32 v0, v0, v46
	ds_bpermute_b32 v46, v110, v0
	ds_read_b128 v[48:51], v242
	ds_read_b128 v[62:65], v222 offset:4096
	v_lshl_add_u64 v[32:33], v[32:33], 0, v[84:85]
	s_waitcnt lgkmcnt(0)
	v_add_f32_e32 v0, v0, v46
	ds_bpermute_b32 v46, v111, v0
	s_waitcnt lgkmcnt(0)
	v_add_f32_e32 v0, v0, v46
	ds_bpermute_b32 v46, v112, v0
	s_waitcnt lgkmcnt(0)
	v_add_f32_e32 v0, v0, v46
	ds_bpermute_b32 v46, v113, v0
	s_waitcnt lgkmcnt(0)
	v_add_f32_e32 v0, v0, v46
	v_fmamk_f32 v0, v0, 0x3a800000, v218
	v_cmp_gt_f32_e32 vcc, s13, v0
	v_mul_f32_e32 v46, 0x4b800000, v0
	s_nop 0
	v_cndmask_b32_e32 v0, v0, v46, vcc
	v_rsq_f32_e32 v0, v0
	s_nop 0
	v_mul_f32_e32 v46, 0x45800000, v0
	v_cndmask_b32_e32 v0, v0, v46, vcc
	v_lshlrev_b64 v[46:47], 11, v[96:97]
	ds_read_b128 v[96:99], v222
	v_mov_b32_e32 v87, v1
	v_mov_b32_e32 v89, v1
	v_mov_b32_e32 v91, v1
	ds_read_b128 v[168:171], v242 offset:1024
	v_lshl_add_u64 v[172:173], v[30:31], 0, v[86:87]
	ds_read_b128 v[172:175], v222 offset:5120
	ds_read_b128 v[176:179], v222 offset:1024
	ds_read_b128 v[180:183], v242 offset:2048
	v_lshl_add_u64 v[184:185], v[30:31], 0, v[88:89]
	ds_read_b128 v[184:187], v222 offset:6144
	ds_read_b128 v[188:191], v222 offset:2048
	ds_read_b128 v[192:195], v242 offset:3072
	v_lshl_add_u64 v[196:197], v[30:31], 0, v[90:91]
	ds_read_b128 v[196:199], v222 offset:7168
	ds_read_b128 v[200:203], v222 offset:3072
	v_pk_mul_f32 v[52:53], v[60:61], v[0:1] op_sel_hi:[1,0]
	v_pk_mul_f32 v[58:59], v[58:59], v[0:1] op_sel_hi:[1,0]
	v_pk_mul_f32 v[44:45], v[44:45], v[0:1] op_sel_hi:[1,0]
	v_pk_mul_f32 v[42:43], v[42:43], v[0:1] op_sel_hi:[1,0]
	v_pk_mul_f32 v[40:41], v[40:41], v[0:1] op_sel_hi:[1,0]
	v_pk_mul_f32 v[38:39], v[38:39], v[0:1] op_sel_hi:[1,0]
	v_pk_mul_f32 v[36:37], v[36:37], v[0:1] op_sel_hi:[1,0]
	v_pk_mul_f32 v[34:35], v[34:35], v[0:1] op_sel_hi:[1,0]
	s_waitcnt vmcnt(11) lgkmcnt(0)
	v_pk_mul_f32 v[48:49], v[48:49], v[58:59]
	v_pk_mul_f32 v[50:51], v[50:51], v[52:53]
	s_waitcnt vmcnt(10) lgkmcnt(0)
	v_pk_add_f32 v[52:53], v[64:65], 1.0 op_sel_hi:[1,0]
	v_pk_add_f32 v[58:59], v[62:63], 1.0 op_sel_hi:[1,0]
	v_lshl_add_u64 v[62:63], v[80:81], 0, v[46:47]
	s_waitcnt vmcnt(9) lgkmcnt(0)
	v_pk_fma_f32 v[50:51], v[52:53], v[50:51], v[98:99]
	v_pk_fma_f32 v[48:49], v[58:59], v[48:49], v[96:97]
	s_nop 0
	v_cvt_pk_bf16_f32 v48, v48, v49
	v_cvt_pk_bf16_f32 v49, v50, v51
	global_store_dwordx2 v[62:63], v[48:49], off
	v_lshl_add_u64 v[50:51], v[30:31], 0, v[86:87]
	s_waitcnt vmcnt(7) lgkmcnt(0)
	v_pk_mul_f32 v[42:43], v[168:169], v[42:43]
	v_pk_mul_f32 v[44:45], v[170:171], v[44:45]
	v_pk_add_f32 v[46:47], v[174:175], 1.0 op_sel_hi:[1, 0]
	v_pk_add_f32 v[48:49], v[172:173], 1.0 op_sel_hi:[1, 0]
	v_pk_fma_f32 v[44:45], v[46:47], v[44:45], v[178:179]
	v_pk_fma_f32 v[42:43], v[48:49], v[42:43], v[176:177]
	v_lshl_add_u64 v[46:47], v[30:31], 0, v[88:89]
	v_cvt_pk_bf16_f32 v42, v42, v43
	v_cvt_pk_bf16_f32 v43, v44, v45
	global_store_dwordx2 v[62:63], v[42:43], off offset:512
	v_lshl_add_u64 v[30:31], v[30:31], 0, v[90:91]
	s_waitcnt vmcnt(5) lgkmcnt(0)
	v_pk_mul_f32 v[38:39], v[180:181], v[38:39]
	v_pk_mul_f32 v[40:41], v[182:183], v[40:41]
	v_pk_add_f32 v[42:43], v[186:187], 1.0 op_sel_hi:[1, 0]
	v_pk_add_f32 v[44:45], v[184:185], 1.0 op_sel_hi:[1, 0]
	v_pk_fma_f32 v[40:41], v[42:43], v[40:41], v[190:191]
	v_pk_fma_f32 v[38:39], v[44:45], v[38:39], v[188:189]
	s_nop 0
	v_cvt_pk_bf16_f32 v38, v38, v39
	v_cvt_pk_bf16_f32 v39, v40, v41
	global_store_dwordx2 v[62:63], v[38:39], off offset:1024
	s_waitcnt vmcnt(3) lgkmcnt(0)
	v_pk_mul_f32 v[34:35], v[34:35], v[192:193]
	v_pk_mul_f32 v[36:37], v[36:37], v[194:195]
	v_pk_add_f32 v[38:39], v[198:199], 1.0 op_sel_hi:[1, 0]
	v_pk_add_f32 v[40:41], v[196:197], 1.0 op_sel_hi:[1, 0]
	v_pk_fma_f32 v[32:33], v[36:37], v[38:39], v[202:203]
	v_pk_fma_f32 v[30:31], v[34:35], v[40:41], v[200:201]
	s_nop 0
	v_cvt_pk_bf16_f32 v30, v30, v31
	v_cvt_pk_bf16_f32 v31, v32, v33
	global_store_dwordx2 v[62:63], v[30:31], off offset:1536
	s_or_b64 exec, exec, s[36:37]
	v_cmp_gt_i32_e32 vcc, s4, v94
	s_and_saveexec_b64 s[36:37], vcc
	s_cbranch_execnz .LBB0_479

.LBB0_479:
	v_mul_f32_e32 v0, v55, v55
	v_mul_f32_e32 v30, v27, v27
	v_fmac_f32_e32 v0, v54, v54
	v_fmac_f32_e32 v30, v26, v26
	v_fmac_f32_e32 v0, v56, v56
	v_fmac_f32_e32 v30, v28, v28
	v_fmac_f32_e32 v0, v57, v57
	v_fmac_f32_e32 v30, v29, v29
	v_add_f32_e32 v0, v30, v0
	v_mul_f32_e32 v30, v19, v19
	v_fmac_f32_e32 v30, v18, v18
	v_fmac_f32_e32 v30, v20, v20
	v_fmac_f32_e32 v30, v21, v21
	v_add_f32_e32 v0, v30, v0
	v_mul_f32_e32 v30, v15, v15
	v_fmac_f32_e32 v30, v14, v14
	v_fmac_f32_e32 v30, v16, v16
	v_fmac_f32_e32 v30, v17, v17
	v_add_f32_e32 v0, v30, v0
	v_min_i32_e32 v30, 0x8000, v94
	v_ashrrev_i32_e32 v30, 12, v30
	v_lshl_add_u32 v222, v30, 13, v223
	v_mul_i32_i24_e32 v30, 0x1800, v30
	v_ashrrev_i32_e32 v31, 31, v30
	v_lshl_add_u64 v[36:37], v[30:31], 2, s[22:23]
	ds_bpermute_b32 v30, v108, v0
	v_lshl_add_u64 v[34:35], v[36:37], 0, s[10:11]
	v_mov_b32_e32 v85, v1
	v_lshl_add_u64 v[38:39], v[34:35], 0, v[84:85]
	ds_read_b128 v[40:43], v222 offset:4096
	s_waitcnt lgkmcnt(0)
	v_add_f32_e32 v0, v0, v30
	ds_bpermute_b32 v30, v109, v0
	v_lshl_add_u64 v[38:39], v[36:37], 0, v[84:85]
	ds_read_b128 v[44:47], v222
	v_ashrrev_i32_e32 v95, 31, v94
	v_lshlrev_b64 v[48:49], 11, v[94:95]
	s_waitcnt lgkmcnt(0)
	v_add_f32_e32 v0, v0, v30
	ds_bpermute_b32 v30, v110, v0
	v_mov_b32_e32 v87, v1
	v_mov_b32_e32 v89, v1
	v_mov_b32_e32 v91, v1
	s_waitcnt lgkmcnt(0)
	v_add_f32_e32 v0, v0, v30
	ds_bpermute_b32 v30, v111, v0
	s_waitcnt lgkmcnt(0)
	v_add_f32_e32 v0, v0, v30
	ds_bpermute_b32 v30, v112, v0
	s_waitcnt lgkmcnt(0)
	v_add_f32_e32 v0, v0, v30
	ds_bpermute_b32 v30, v113, v0
	s_waitcnt lgkmcnt(0)
	v_add_f32_e32 v0, v0, v30
	v_fmamk_f32 v0, v0, 0x3a800000, v218
	v_cmp_gt_f32_e32 vcc, s13, v0
	v_mul_f32_e32 v30, 0x4b800000, v0
	s_waitcnt vmcnt(1) lgkmcnt(0)
	v_pk_add_f32 v[40:41], v[40:41], 1.0 op_sel_hi:[1,0]
	v_cndmask_b32_e32 v0, v0, v30, vcc
	v_rsq_f32_e32 v0, v0
	s_nop 0
	v_mul_f32_e32 v30, 0x45800000, v0
	v_cndmask_b32_e32 v0, v0, v30, vcc
	ds_read_b128 v[30:33], v242
	v_mov_b32_e32 v87, v1
	v_mov_b32_e32 v89, v1
	v_mov_b32_e32 v91, v1
	ds_read_b128 v[168:171], v242 offset:1024
	v_lshl_add_u64 v[172:173], v[34:35], 0, v[86:87]
	ds_read_b128 v[172:175], v222 offset:5120
	ds_read_b128 v[176:179], v222 offset:1024
	ds_read_b128 v[180:183], v242 offset:2048
	v_lshl_add_u64 v[184:185], v[34:35], 0, v[88:89]
	ds_read_b128 v[184:187], v222 offset:6144
	ds_read_b128 v[188:191], v222 offset:2048
	ds_read_b128 v[192:195], v242 offset:3072
	v_lshl_add_u64 v[196:197], v[34:35], 0, v[90:91]
	ds_read_b128 v[196:199], v222 offset:7168
	ds_read_b128 v[200:203], v222 offset:3072
	v_pk_mul_f32 v[36:37], v[56:57], v[0:1] op_sel_hi:[1,0]
	v_pk_mul_f32 v[50:51], v[54:55], v[0:1] op_sel_hi:[1,0]
	v_pk_mul_f32 v[28:29], v[28:29], v[0:1] op_sel_hi:[1,0]
	v_pk_mul_f32 v[26:27], v[26:27], v[0:1] op_sel_hi:[1,0]
	v_pk_mul_f32 v[20:21], v[20:21], v[0:1] op_sel_hi:[1,0]
	v_pk_mul_f32 v[18:19], v[18:19], v[0:1] op_sel_hi:[1,0]
	v_pk_mul_f32 v[16:17], v[16:17], v[0:1] op_sel_hi:[1,0]
	v_pk_mul_f32 v[14:15], v[14:15], v[0:1] op_sel_hi:[1,0]
	s_waitcnt vmcnt(9) lgkmcnt(0)
	v_pk_mul_f32 v[30:31], v[30:31], v[50:51]
	v_pk_mul_f32 v[32:33], v[32:33], v[36:37]
	v_pk_add_f32 v[36:37], v[42:43], 1.0 op_sel_hi:[1,0]
	v_pk_fma_f32 v[30:31], v[40:41], v[30:31], v[44:45]
	v_pk_fma_f32 v[32:33], v[36:37], v[32:33], v[46:47]
	v_cvt_pk_bf16_f32 v30, v30, v31
	v_cvt_pk_bf16_f32 v31, v32, v33
	v_lshl_add_u64 v[36:37], v[80:81], 0, v[48:49]
	global_store_dwordx2 v[36:37], v[30:31], off
	v_lshl_add_u64 v[40:41], v[34:35], 0, v[86:87]
	s_waitcnt vmcnt(7) lgkmcnt(0)
	v_pk_mul_f32 v[26:27], v[168:169], v[26:27]
	v_pk_mul_f32 v[28:29], v[170:171], v[28:29]
	v_pk_add_f32 v[30:31], v[174:175], 1.0 op_sel_hi:[1, 0]
	v_pk_add_f32 v[32:33], v[172:173], 1.0 op_sel_hi:[1, 0]
	v_pk_fma_f32 v[28:29], v[30:31], v[28:29], v[178:179]
	v_pk_fma_f32 v[26:27], v[32:33], v[26:27], v[176:177]
	v_lshl_add_u64 v[30:31], v[34:35], 0, v[88:89]
	v_cvt_pk_bf16_f32 v26, v26, v27
	v_cvt_pk_bf16_f32 v27, v28, v29
	global_store_dwordx2 v[36:37], v[26:27], off offset:512
	s_waitcnt vmcnt(5) lgkmcnt(0)
	v_pk_mul_f32 v[18:19], v[180:181], v[18:19]
	v_pk_mul_f32 v[20:21], v[182:183], v[20:21]
	v_pk_add_f32 v[26:27], v[186:187], 1.0 op_sel_hi:[1, 0]
	v_pk_add_f32 v[28:29], v[184:185], 1.0 op_sel_hi:[1, 0]
	v_pk_fma_f32 v[20:21], v[26:27], v[20:21], v[190:191]
	v_pk_fma_f32 v[18:19], v[28:29], v[18:19], v[188:189]
	v_lshl_add_u64 v[26:27], v[34:35], 0, v[90:91]
	v_cvt_pk_bf16_f32 v18, v18, v19
	v_cvt_pk_bf16_f32 v19, v20, v21
	global_store_dwordx2 v[36:37], v[18:19], off offset:1024
	s_waitcnt vmcnt(3) lgkmcnt(0)
	v_pk_mul_f32 v[14:15], v[14:15], v[192:193]
	v_pk_mul_f32 v[16:17], v[16:17], v[194:195]
	v_pk_add_f32 v[18:19], v[198:199], 1.0 op_sel_hi:[1, 0]
	v_pk_add_f32 v[20:21], v[196:197], 1.0 op_sel_hi:[1, 0]
	v_pk_fma_f32 v[16:17], v[16:17], v[18:19], v[202:203]
	v_pk_fma_f32 v[14:15], v[14:15], v[20:21], v[200:201]
	s_nop 0
	v_cvt_pk_bf16_f32 v14, v14, v15
	v_cvt_pk_bf16_f32 v15, v16, v17
	global_store_dwordx2 v[36:37], v[14:15], off offset:1536
	s_or_b64 exec, exec, s[36:37]
	v_cmp_gt_i32_e32 vcc, s4, v92
	s_and_saveexec_b64 s[36:37], vcc
	s_cbranch_execz .LBB0_442
.LBB0_480:
	v_mul_f32_e32 v0, v23, v23
	v_mul_f32_e32 v14, v11, v11
	v_fmac_f32_e32 v0, v22, v22
	v_fmac_f32_e32 v14, v10, v10
	v_fmac_f32_e32 v0, v24, v24
	v_fmac_f32_e32 v14, v12, v12
	v_fmac_f32_e32 v0, v25, v25
	v_fmac_f32_e32 v14, v13, v13
	v_add_f32_e32 v0, v14, v0
	v_mul_f32_e32 v14, v7, v7
	v_fmac_f32_e32 v14, v6, v6
	v_fmac_f32_e32 v14, v8, v8
	v_fmac_f32_e32 v14, v9, v9
	v_add_f32_e32 v0, v14, v0
	v_mul_f32_e32 v14, v3, v3
	v_fmac_f32_e32 v14, v2, v2
	v_fmac_f32_e32 v14, v4, v4
	v_fmac_f32_e32 v14, v5, v5
	v_add_f32_e32 v0, v14, v0
	v_min_i32_e32 v14, 0x8000, v92
	v_ashrrev_i32_e32 v14, 12, v14
	v_lshl_add_u32 v222, v14, 13, v223
	v_mul_i32_i24_e32 v14, 0x1800, v14
	v_ashrrev_i32_e32 v15, 31, v14
	v_lshl_add_u64 v[20:21], v[14:15], 2, s[22:23]
	ds_bpermute_b32 v14, v108, v0
	v_lshl_add_u64 v[18:19], v[20:21], 0, s[10:11]
	v_mov_b32_e32 v85, v1
	v_lshl_add_u64 v[26:27], v[18:19], 0, v[84:85]
	ds_read_b128 v[28:31], v222 offset:4096
	s_waitcnt lgkmcnt(0)
	v_add_f32_e32 v0, v0, v14
	ds_bpermute_b32 v14, v109, v0
	v_lshl_add_u64 v[26:27], v[20:21], 0, v[84:85]
	ds_read_b128 v[32:35], v222
	v_ashrrev_i32_e32 v93, 31, v92
	v_lshlrev_b64 v[36:37], 11, v[92:93]
	s_waitcnt lgkmcnt(0)
	v_add_f32_e32 v0, v0, v14
	ds_bpermute_b32 v14, v110, v0
	v_mov_b32_e32 v87, v1
	v_mov_b32_e32 v89, v1
	v_mov_b32_e32 v91, v1
	s_waitcnt lgkmcnt(0)
	v_add_f32_e32 v0, v0, v14
	ds_bpermute_b32 v14, v111, v0
	s_waitcnt lgkmcnt(0)
	v_add_f32_e32 v0, v0, v14
	ds_bpermute_b32 v14, v112, v0
	s_waitcnt lgkmcnt(0)
	v_add_f32_e32 v0, v0, v14
	ds_bpermute_b32 v14, v113, v0
	s_waitcnt lgkmcnt(0)
	v_add_f32_e32 v0, v0, v14
	v_fmamk_f32 v0, v0, 0x3a800000, v218
	v_cmp_gt_f32_e32 vcc, s13, v0
	v_mul_f32_e32 v14, 0x4b800000, v0
	s_nop 0
	v_cndmask_b32_e32 v0, v0, v14, vcc
	v_rsq_f32_e32 v0, v0
	s_nop 0
	v_mul_f32_e32 v14, 0x45800000, v0
	v_cndmask_b32_e32 v0, v0, v14, vcc
	ds_read_b128 v[14:17], v242
	v_mov_b32_e32 v87, v1
	v_mov_b32_e32 v89, v1
	v_mov_b32_e32 v91, v1
	ds_read_b128 v[168:171], v242 offset:1024
	v_lshl_add_u64 v[172:173], v[18:19], 0, v[86:87]
	ds_read_b128 v[172:175], v222 offset:5120
	ds_read_b128 v[176:179], v222 offset:1024
	ds_read_b128 v[180:183], v242 offset:2048
	v_lshl_add_u64 v[184:185], v[18:19], 0, v[88:89]
	ds_read_b128 v[184:187], v222 offset:6144
	ds_read_b128 v[188:191], v222 offset:2048
	ds_read_b128 v[192:195], v242 offset:3072
	v_lshl_add_u64 v[196:197], v[18:19], 0, v[90:91]
	ds_read_b128 v[196:199], v222 offset:7168
	ds_read_b128 v[200:203], v222 offset:3072
	v_pk_mul_f32 v[20:21], v[24:25], v[0:1] op_sel_hi:[1,0]
	v_pk_mul_f32 v[22:23], v[22:23], v[0:1] op_sel_hi:[1,0]
	v_pk_mul_f32 v[12:13], v[12:13], v[0:1] op_sel_hi:[1,0]
	v_pk_mul_f32 v[10:11], v[10:11], v[0:1] op_sel_hi:[1,0]
	v_pk_mul_f32 v[8:9], v[8:9], v[0:1] op_sel_hi:[1,0]
	v_pk_mul_f32 v[6:7], v[6:7], v[0:1] op_sel_hi:[1,0]
	v_pk_mul_f32 v[4:5], v[4:5], v[0:1] op_sel_hi:[1,0]
	v_pk_mul_f32 v[2:3], v[2:3], v[0:1] op_sel_hi:[1,0]
	s_waitcnt vmcnt(9) lgkmcnt(0)
	v_pk_mul_f32 v[14:15], v[14:15], v[22:23]
	v_pk_mul_f32 v[16:17], v[16:17], v[20:21]
	v_pk_add_f32 v[20:21], v[30:31], 1.0 op_sel_hi:[1,0]
	v_pk_add_f32 v[22:23], v[28:29], 1.0 op_sel_hi:[1,0]
	v_pk_fma_f32 v[16:17], v[20:21], v[16:17], v[34:35]
	v_pk_fma_f32 v[14:15], v[22:23], v[14:15], v[32:33]
	v_lshl_add_u64 v[20:21], v[80:81], 0, v[36:37]
	v_cvt_pk_bf16_f32 v14, v14, v15
	v_cvt_pk_bf16_f32 v15, v16, v17
	global_store_dwordx2 v[20:21], v[14:15], off
	v_lshl_add_u64 v[22:23], v[18:19], 0, v[86:87]
	s_waitcnt vmcnt(7) lgkmcnt(0)
	v_pk_mul_f32 v[10:11], v[168:169], v[10:11]
	v_pk_mul_f32 v[12:13], v[170:171], v[12:13]
	v_pk_add_f32 v[14:15], v[174:175], 1.0 op_sel_hi:[1, 0]
	v_pk_add_f32 v[16:17], v[172:173], 1.0 op_sel_hi:[1, 0]
	v_pk_fma_f32 v[12:13], v[14:15], v[12:13], v[178:179]
	v_pk_fma_f32 v[10:11], v[16:17], v[10:11], v[176:177]
	v_lshl_add_u64 v[14:15], v[18:19], 0, v[88:89]
	v_cvt_pk_bf16_f32 v10, v10, v11
	v_cvt_pk_bf16_f32 v11, v12, v13
	global_store_dwordx2 v[20:21], v[10:11], off offset:512
	s_waitcnt vmcnt(5) lgkmcnt(0)
	v_pk_mul_f32 v[6:7], v[180:181], v[6:7]
	v_pk_mul_f32 v[8:9], v[182:183], v[8:9]
	v_pk_add_f32 v[10:11], v[186:187], 1.0 op_sel_hi:[1, 0]
	v_pk_add_f32 v[12:13], v[184:185], 1.0 op_sel_hi:[1, 0]
	v_pk_fma_f32 v[8:9], v[10:11], v[8:9], v[190:191]
	v_pk_fma_f32 v[6:7], v[12:13], v[6:7], v[188:189]
	v_lshl_add_u64 v[10:11], v[18:19], 0, v[90:91]
	v_cvt_pk_bf16_f32 v6, v6, v7
	v_cvt_pk_bf16_f32 v7, v8, v9
	global_store_dwordx2 v[20:21], v[6:7], off offset:1024
	s_waitcnt vmcnt(3) lgkmcnt(0)
	v_pk_mul_f32 v[2:3], v[2:3], v[192:193]
	v_pk_mul_f32 v[4:5], v[4:5], v[194:195]
	v_pk_add_f32 v[6:7], v[198:199], 1.0 op_sel_hi:[1, 0]
	v_pk_add_f32 v[8:9], v[196:197], 1.0 op_sel_hi:[1, 0]
	v_pk_fma_f32 v[4:5], v[4:5], v[6:7], v[202:203]
	v_pk_fma_f32 v[2:3], v[2:3], v[8:9], v[200:201]
	s_nop 0
	v_cvt_pk_bf16_f32 v2, v2, v3
	v_cvt_pk_bf16_f32 v3, v4, v5
	global_store_dwordx2 v[20:21], v[2:3], off offset:1536
	s_branch .LBB0_442
	s_nop 0
	s_nop 0
	s_nop 0
	s_nop 0
	s_nop 0
	s_nop 0
	s_nop 0
	s_nop 0
	s_nop 0
	s_nop 0
	s_nop 0
	s_nop 0
	s_nop 0
	s_nop 0
	s_nop 0
	s_nop 0
	s_nop 0
	s_nop 0
	s_nop 0
	s_nop 0
	s_nop 0
	s_nop 0
	s_nop 0
	s_nop 0
	s_nop 0
	s_nop 0
	s_nop 0
	s_nop 0
	s_nop 0
	s_nop 0
	s_nop 0
	s_nop 0
	s_nop 0
	s_nop 0
	s_nop 0
	s_nop 0
	s_nop 0
	s_nop 0
	s_nop 0
	s_nop 0
	s_nop 0
	s_nop 0
	s_nop 0
	s_nop 0
	s_nop 0
	s_nop 0
	s_nop 0
	s_nop 0
	s_nop 0
	s_nop 0
	s_nop 0
	s_nop 0
	s_nop 0
	s_nop 0
	s_nop 0
	s_nop 0
	s_nop 0
	s_nop 0
	s_nop 0
	s_nop 0
	s_nop 0
	s_nop 0
	s_nop 0
	s_nop 0
	s_nop 0
	s_nop 0
	s_nop 0
	s_nop 0
	s_nop 0
	s_nop 0
	s_nop 0
	s_nop 0
	s_nop 0
	s_nop 0
	s_nop 0
	s_nop 0

.LBB0_527:
	v_ashrrev_i32_e32 v0, 6, v166
	v_readlane_b32 s0, v252, 17
	s_nop 1
	v_add_u32_e32 v66, s0, v0
	v_cmp_gt_i32_e32 vcc, s15, v66
	s_and_saveexec_b64 s[0:1], vcc
	s_cbranch_execz .LBB0_568
	v_and_b32_e32 v3, 64, v220
	v_add_u32_e32 v3, 64, v3
	v_xor_b32_e32 v5, 32, v220
	v_cmp_lt_i32_e32 vcc, v5, v3
	s_waitcnt lgkmcnt(0)
	s_load_dword s8, s[96:97], 0x0
	v_readlane_b32 s2, v254, 57
	v_cndmask_b32_e32 v5, v220, v5, vcc
	v_lshlrev_b32_e32 v102, 2, v5
	v_xor_b32_e32 v5, 16, v220
	v_cmp_lt_i32_e32 vcc, v5, v3
	v_readlane_b32 s3, v254, 58
	s_lshl_b32 s2, s2, 10
	v_cndmask_b32_e32 v5, v220, v5, vcc
	v_lshlrev_b32_e32 v103, 2, v5
	v_xor_b32_e32 v5, 8, v220
	v_cmp_lt_i32_e32 vcc, v5, v3
	s_ashr_i32 s3, s2, 31
	v_lshlrev_b32_e32 v0, 2, v166
	v_cndmask_b32_e32 v5, v220, v5, vcc
	v_lshlrev_b32_e32 v104, 2, v5
	v_xor_b32_e32 v5, 4, v220
	v_cmp_lt_i32_e32 vcc, v5, v3
	s_lshl_b64 s[2:3], s[2:3], 2
	s_waitcnt lgkmcnt(0)
	s_lshl_b32 s4, s8, 3
	v_cndmask_b32_e32 v5, v220, v5, vcc
	s_add_u32 s6, s84, s2
	v_and_b32_e32 v2, 0xfc, v0
	v_lshlrev_b32_e32 v105, 2, v5
	v_xor_b32_e32 v5, 2, v220
	s_addc_u32 s7, s85, s3
	v_lshlrev_b32_e32 v0, 2, v2
	v_cmp_lt_i32_e32 vcc, v5, v3
	v_lshl_add_u64 v[70:71], s[6:7], 0, v[0:1]
	v_readlane_b32 s6, v253, 39
	v_cndmask_b32_e32 v5, v220, v5, vcc
	s_cmp_lg_u64 s[30:31], 0
	v_lshl_add_u64 v[68:69], s[30:31], 0, v[0:1]
	v_lshlrev_b32_e32 v106, 2, v5
	v_xor_b32_e32 v5, 1, v220
	v_lshl_add_u64 v[72:73], s[54:55], 0, v[0:1]
	v_lshlrev_b32_e32 v0, 1, v2
	v_readlane_b32 s7, v253, 40
	v_ashrrev_i32_e32 v67, 31, v66
	s_cselect_b64 s[22:23], -1, 0
	s_lshl_b32 s24, s8, 5
	v_cmp_lt_i32_e32 vcc, v5, v3
	v_lshl_add_u64 v[74:75], s[6:7], 0, v[0:1]
	v_lshlrev_b64 v[10:11], 11, v[66:67]
	v_and_b32_e32 v0, 63, v166
	v_or_b32_e32 v4, 0x100, v2
	v_or_b32_e32 v6, 0x200, v2
	v_or_b32_e32 v8, 0x300, v2
	v_cndmask_b32_e32 v3, v220, v5, vcc
	v_lshl_or_b32 v10, v0, 3, v10
	s_ashr_i32 s25, s24, 31
	s_mov_b64 s[2:3], 0
	v_lshlrev_b32_e32 v107, 2, v3
	v_lshl_add_u64 v[76:77], s[6:7], 0, v[10:11]
	s_lshl_b64 s[30:31], s[24:25], 11
	s_lshl_b32 s5, s8, 4
	s_mul_i32 s6, s8, 24
	v_lshlrev_b32_e32 v78, 2, v2
	v_lshlrev_b32_e32 v80, 2, v4
	v_lshlrev_b32_e32 v82, 2, v6
	v_lshlrev_b32_e32 v84, 2, v8
	v_and_b32_e32 v223, 63, v166
	v_lshlrev_b32_e32 v223, 4, v223
	v_add_u32_e32 v242, 0x12000, v223
	v_lshlrev_b32_e32 v50, 4, v166
	s_mov_b64 s[98:99], s[44:45]
	global_load_dwordx4 v[10:13], v50, s[98:99]
	s_add_u32 s98, s98, 0x6000
	s_addc_u32 s99, s99, 0
	global_load_dwordx4 v[14:17], v50, s[98:99]
	s_add_u32 s98, s98, 0x6000
	s_addc_u32 s99, s99, 0
	global_load_dwordx4 v[18:21], v50, s[98:99]
	s_add_u32 s98, s98, 0x6000
	s_addc_u32 s99, s99, 0
	global_load_dwordx4 v[22:25], v50, s[98:99]
	s_add_u32 s98, s98, 0x6000
	s_addc_u32 s99, s99, 0
	global_load_dwordx4 v[26:29], v50, s[98:99]
	s_add_u32 s98, s98, 0x6000
	s_addc_u32 s99, s99, 0
	global_load_dwordx4 v[30:33], v50, s[98:99]
	s_add_u32 s98, s98, 0x6000
	s_addc_u32 s99, s99, 0
	global_load_dwordx4 v[34:37], v50, s[98:99]
	s_add_u32 s98, s98, 0x6000
	s_addc_u32 s99, s99, 0
	global_load_dwordx4 v[38:41], v50, s[98:99]
	s_add_u32 s98, s98, 0x6000
	s_addc_u32 s99, s99, 0
	global_load_dwordx4 v[42:45], v50, s[98:99]
	s_add_u32 s98, s98, 0x6000
	s_addc_u32 s99, s99, 0
	v_lshrrev_b32_e32 v54, 6, v166
	v_lshlrev_b32_e32 v54, 10, v54
	v_mov_b32_e32 v55, 0
	v_lshl_add_u64 v[52:53], v[70:71], 0, v[54:55]
	v_add_u32_e32 v51, 0x12000, v50
	v_cmp_gt_u32_e32 vcc, 0x100, v166
	s_and_saveexec_b64 s[98:99], vcc
	global_load_dwordx4 v[46:49], v[52:53], off
	s_waitcnt vmcnt(0)
	ds_write_b128 v51, v[46:49]
	s_mov_b64 exec, s[98:99]
	ds_write_b128 v50, v[10:13]
	v_add_u32_e32 v50, 0x2000, v50
	ds_write_b128 v50, v[14:17]
	v_add_u32_e32 v50, 0x2000, v50
	ds_write_b128 v50, v[18:21]
	v_add_u32_e32 v50, 0x2000, v50
	ds_write_b128 v50, v[22:25]
	v_add_u32_e32 v50, 0x2000, v50
	ds_write_b128 v50, v[26:29]
	v_add_u32_e32 v50, 0x2000, v50
	ds_write_b128 v50, v[30:33]
	v_add_u32_e32 v50, 0x2000, v50
	ds_write_b128 v50, v[34:37]
	v_add_u32_e32 v50, 0x2000, v50
	ds_write_b128 v50, v[38:41]
	v_add_u32_e32 v50, 0x2000, v50
	ds_write_b128 v50, v[42:45]
	s_waitcnt lgkmcnt(0)
	s_barrier
	s_branch .LBB0_530

.LBB0_562:
	s_or_b64 exec, exec, s[34:35]
	v_min_i32_e32 v0, 0x8000, v66
	v_ashrrev_i32_e32 v0, 12, v0
	v_lshl_add_u32 v222, v0, 13, v223
	v_mul_i32_i24_e32 v92, 0x1800, v0
	v_ashrrev_i32_e32 v93, 31, v92
	v_lshl_add_u64 v[100:101], v[92:93], 2, s[44:45]
	s_mov_b64 s[8:9], 0x1000
	v_lshl_add_u64 v[112:113], v[100:101], 0, s[8:9]
	v_mov_b32_e32 v79, v1
	v_lshl_add_u64 v[96:97], v[112:113], 0, v[78:79]
	ds_read_b128 v[92:95], v242
	v_lshl_add_u64 v[100:101], v[100:101], 0, v[78:79]
	ds_read_b128 v[96:99], v222 offset:4096
	s_waitcnt vmcnt(0) lgkmcnt(0)
	v_mul_f32_e32 v0, v39, v39
	ds_read_b128 v[108:111], v222
	v_mov_b32_e32 v81, v1
	v_mov_b32_e32 v83, v1
	v_mov_b32_e32 v85, v1
	ds_read_b128 v[168:171], v242 offset:1024
	v_lshl_add_u64 v[172:173], v[112:113], 0, v[80:81]
	ds_read_b128 v[172:175], v222 offset:5120
	ds_read_b128 v[176:179], v222 offset:1024
	ds_read_b128 v[180:183], v242 offset:2048
	v_lshl_add_u64 v[184:185], v[112:113], 0, v[82:83]
	ds_read_b128 v[184:187], v222 offset:6144
	ds_read_b128 v[188:191], v222 offset:2048
	ds_read_b128 v[192:195], v242 offset:3072
	v_lshl_add_u64 v[196:197], v[112:113], 0, v[84:85]
	ds_read_b128 v[196:199], v222 offset:7168
	ds_read_b128 v[200:203], v222 offset:3072
	v_mul_f32_e32 v81, v23, v23
	v_mul_f32_e32 v83, v7, v7
	v_fmac_f32_e32 v0, v38, v38
	v_fmac_f32_e32 v81, v22, v22
	v_mul_f32_e32 v85, v3, v3
	v_fmac_f32_e32 v83, v6, v6
	v_fmac_f32_e32 v0, v40, v40
	v_fmac_f32_e32 v81, v24, v24
	v_fmac_f32_e32 v85, v2, v2
	v_fmac_f32_e32 v83, v8, v8
	v_fmac_f32_e32 v0, v41, v41
	v_fmac_f32_e32 v81, v25, v25
	v_fmac_f32_e32 v85, v4, v4
	v_fmac_f32_e32 v83, v9, v9
	v_add_f32_e32 v0, v81, v0
	v_fmac_f32_e32 v85, v5, v5
	v_add_f32_e32 v0, v83, v0
	v_add_f32_e32 v0, v85, v0
	ds_bpermute_b32 v81, v102, v0
	v_mov_b32_e32 v85, v1
	s_waitcnt lgkmcnt(0)
	v_add_f32_e32 v0, v0, v81
	ds_bpermute_b32 v81, v103, v0
	s_waitcnt lgkmcnt(0)
	v_add_f32_e32 v0, v0, v81
	ds_bpermute_b32 v81, v104, v0
	s_waitcnt lgkmcnt(0)
	v_add_f32_e32 v0, v0, v81
	ds_bpermute_b32 v81, v105, v0
	s_waitcnt lgkmcnt(0)
	v_add_f32_e32 v0, v0, v81
	ds_bpermute_b32 v81, v106, v0
	s_waitcnt lgkmcnt(0)
	v_add_f32_e32 v0, v0, v81
	ds_bpermute_b32 v81, v107, v0
	s_waitcnt lgkmcnt(0)
	v_add_f32_e32 v0, v0, v81
	v_fmamk_f32 v0, v0, 0x3a800000, v218
	v_mul_f32_e32 v81, 0x4b800000, v0
	v_cmp_gt_f32_e32 vcc, s13, v0
	s_nop 1
	v_cndmask_b32_e32 v0, v0, v81, vcc
	v_rsq_f32_e32 v0, v0
	v_mov_b32_e32 v81, v1
	v_mul_f32_e32 v83, 0x45800000, v0
	v_cndmask_b32_e32 v0, v0, v83, vcc
	v_pk_mul_f32 v[40:41], v[40:41], v[0:1] op_sel_hi:[1,0]
	v_pk_mul_f32 v[38:39], v[38:39], v[0:1] op_sel_hi:[1,0]
	v_pk_mul_f32 v[24:25], v[24:25], v[0:1] op_sel_hi:[1,0]
	v_pk_mul_f32 v[22:23], v[22:23], v[0:1] op_sel_hi:[1,0]
	v_mov_b32_e32 v83, v1
	v_pk_mul_f32 v[8:9], v[8:9], v[0:1] op_sel_hi:[1,0]
	v_pk_mul_f32 v[6:7], v[6:7], v[0:1] op_sel_hi:[1,0]
	v_pk_mul_f32 v[4:5], v[4:5], v[0:1] op_sel_hi:[1,0]
	v_pk_mul_f32 v[2:3], v[2:3], v[0:1] op_sel_hi:[1,0]
	v_pk_mul_f32 v[38:39], v[92:93], v[38:39]
	v_pk_mul_f32 v[40:41], v[94:95], v[40:41]
	v_pk_add_f32 v[92:93], v[98:99], 1.0 op_sel_hi:[1,0]
	v_pk_add_f32 v[94:95], v[96:97], 1.0 op_sel_hi:[1,0]
	s_waitcnt vmcnt(9) lgkmcnt(0)
	v_pk_fma_f32 v[40:41], v[92:93], v[40:41], v[110:111]
	v_pk_fma_f32 v[38:39], v[94:95], v[38:39], v[108:109]
	v_lshl_add_u64 v[92:93], v[112:113], 0, v[80:81]
	v_cvt_pk_bf16_f32 v38, v38, v39
	v_cvt_pk_bf16_f32 v39, v40, v41
	global_store_dwordx2 v[76:77], v[38:39], off
	v_cmp_gt_i32_e32 vcc, s15, v86
	s_waitcnt vmcnt(7) lgkmcnt(0)
	v_pk_mul_f32 v[22:23], v[168:169], v[22:23]
	v_pk_mul_f32 v[24:25], v[170:171], v[24:25]
	v_pk_add_f32 v[38:39], v[174:175], 1.0 op_sel_hi:[1, 0]
	v_pk_add_f32 v[40:41], v[172:173], 1.0 op_sel_hi:[1, 0]
	v_pk_fma_f32 v[24:25], v[38:39], v[24:25], v[178:179]
	v_pk_fma_f32 v[22:23], v[40:41], v[22:23], v[176:177]
	v_lshl_add_u64 v[38:39], v[112:113], 0, v[82:83]
	v_cvt_pk_bf16_f32 v22, v22, v23
	v_cvt_pk_bf16_f32 v23, v24, v25
	global_store_dwordx2 v[76:77], v[22:23], off offset:512
	s_waitcnt vmcnt(5) lgkmcnt(0)
	v_pk_mul_f32 v[6:7], v[180:181], v[6:7]
	v_pk_mul_f32 v[8:9], v[182:183], v[8:9]
	v_pk_add_f32 v[22:23], v[186:187], 1.0 op_sel_hi:[1, 0]
	v_pk_add_f32 v[24:25], v[184:185], 1.0 op_sel_hi:[1, 0]
	v_pk_fma_f32 v[8:9], v[22:23], v[8:9], v[190:191]
	v_pk_fma_f32 v[6:7], v[24:25], v[6:7], v[188:189]
	v_lshl_add_u64 v[22:23], v[112:113], 0, v[84:85]
	v_cvt_pk_bf16_f32 v6, v6, v7
	v_cvt_pk_bf16_f32 v7, v8, v9
	global_store_dwordx2 v[76:77], v[6:7], off offset:1024
	s_waitcnt vmcnt(3) lgkmcnt(0)
	v_pk_mul_f32 v[2:3], v[2:3], v[192:193]
	v_pk_mul_f32 v[4:5], v[4:5], v[194:195]
	v_pk_add_f32 v[6:7], v[198:199], 1.0 op_sel_hi:[1, 0]
	v_pk_add_f32 v[8:9], v[196:197], 1.0 op_sel_hi:[1, 0]
	v_pk_fma_f32 v[4:5], v[4:5], v[6:7], v[202:203]
	v_pk_fma_f32 v[2:3], v[2:3], v[8:9], v[200:201]
	s_nop 0
	v_cvt_pk_bf16_f32 v2, v2, v3
	v_cvt_pk_bf16_f32 v3, v4, v5
	global_store_dwordx2 v[76:77], v[2:3], off offset:1536
	s_and_saveexec_b64 s[34:35], vcc
	s_cbranch_execz .LBB0_565
	v_min_i32_e32 v0, 0x8000, v86
	v_ashrrev_i32_e32 v0, 12, v0
	v_lshl_add_u32 v222, v0, 13, v223
	v_mul_i32_i24_e32 v2, 0x1800, v0
	v_ashrrev_i32_e32 v3, 31, v2
	v_lshl_add_u64 v[22:23], v[2:3], 2, s[44:45]
	v_lshl_add_u64 v[38:39], v[22:23], 0, s[8:9]
	v_lshl_add_u64 v[6:7], v[38:39], 0, v[78:79]
	ds_read_b128 v[2:5], v242
	v_lshl_add_u64 v[40:41], v[22:23], 0, v[78:79]
	ds_read_b128 v[6:9], v222 offset:4096
	v_mul_f32_e32 v0, v35, v35
	ds_read_b128 v[22:25], v222
	v_mov_b32_e32 v81, v1
	v_mov_b32_e32 v83, v1
	v_mov_b32_e32 v85, v1
	ds_read_b128 v[168:171], v242 offset:1024
	v_lshl_add_u64 v[172:173], v[38:39], 0, v[80:81]
	ds_read_b128 v[172:175], v222 offset:5120
	ds_read_b128 v[176:179], v222 offset:1024
	ds_read_b128 v[180:183], v242 offset:2048
	v_lshl_add_u64 v[184:185], v[38:39], 0, v[82:83]
	ds_read_b128 v[184:187], v222 offset:6144
	ds_read_b128 v[188:191], v222 offset:2048
	ds_read_b128 v[192:195], v242 offset:3072
	v_lshl_add_u64 v[196:197], v[38:39], 0, v[84:85]
	ds_read_b128 v[196:199], v222 offset:7168
	ds_read_b128 v[200:203], v222 offset:3072
	v_mul_f32_e32 v79, v31, v31
	v_mul_f32_e32 v87, v19, v19
	v_fmac_f32_e32 v0, v34, v34
	v_fmac_f32_e32 v79, v30, v30
	v_mul_f32_e32 v89, v11, v11
	v_fmac_f32_e32 v87, v18, v18
	v_fmac_f32_e32 v0, v36, v36
	v_fmac_f32_e32 v79, v32, v32
	v_fmac_f32_e32 v89, v10, v10
	v_fmac_f32_e32 v87, v20, v20
	v_fmac_f32_e32 v0, v37, v37
	v_fmac_f32_e32 v79, v33, v33
	v_fmac_f32_e32 v89, v12, v12
	v_fmac_f32_e32 v87, v21, v21
	v_add_f32_e32 v0, v79, v0
	v_fmac_f32_e32 v89, v13, v13
	v_add_f32_e32 v0, v87, v0
	v_add_f32_e32 v0, v89, v0
	ds_bpermute_b32 v79, v102, v0
	v_ashrrev_i32_e32 v87, 31, v86
	v_lshlrev_b64 v[86:87], 11, v[86:87]
	v_lshl_add_u64 v[86:87], v[74:75], 0, v[86:87]
	s_waitcnt lgkmcnt(0)
	v_add_f32_e32 v0, v0, v79
	ds_bpermute_b32 v79, v103, v0
	s_waitcnt lgkmcnt(0)
	v_add_f32_e32 v0, v0, v79
	ds_bpermute_b32 v79, v104, v0
	s_waitcnt lgkmcnt(0)
	v_add_f32_e32 v0, v0, v79
	ds_bpermute_b32 v79, v105, v0
	s_waitcnt lgkmcnt(0)
	v_add_f32_e32 v0, v0, v79
	ds_bpermute_b32 v79, v106, v0
	s_waitcnt lgkmcnt(0)
	v_add_f32_e32 v0, v0, v79
	ds_bpermute_b32 v79, v107, v0
	s_waitcnt lgkmcnt(0)
	v_add_f32_e32 v0, v0, v79
	v_fmamk_f32 v0, v0, 0x3a800000, v218
	v_mul_f32_e32 v79, 0x4b800000, v0
	v_cmp_gt_f32_e32 vcc, s13, v0
	s_waitcnt vmcnt(10) lgkmcnt(0)
	v_pk_add_f32 v[8:9], v[8:9], 1.0 op_sel_hi:[1,0]
	v_cndmask_b32_e32 v0, v0, v79, vcc
	v_rsq_f32_e32 v0, v0
	v_pk_add_f32 v[6:7], v[6:7], 1.0 op_sel_hi:[1,0]
	v_mul_f32_e32 v79, 0x45800000, v0
	v_cndmask_b32_e32 v0, v0, v79, vcc
	v_pk_mul_f32 v[36:37], v[36:37], v[0:1] op_sel_hi:[1,0]
	v_pk_mul_f32 v[34:35], v[34:35], v[0:1] op_sel_hi:[1,0]
	v_pk_mul_f32 v[4:5], v[4:5], v[36:37]
	v_pk_mul_f32 v[2:3], v[2:3], v[34:35]
	s_waitcnt vmcnt(9) lgkmcnt(0)
	v_pk_fma_f32 v[4:5], v[8:9], v[4:5], v[24:25]
	v_pk_fma_f32 v[2:3], v[6:7], v[2:3], v[22:23]
	v_lshl_add_u64 v[6:7], v[38:39], 0, v[80:81]
	v_cvt_pk_bf16_f32 v2, v2, v3
	v_cvt_pk_bf16_f32 v3, v4, v5
	global_store_dwordx2 v[86:87], v[2:3], off
	v_pk_mul_f32 v[32:33], v[32:33], v[0:1] op_sel_hi:[1,0]
	v_pk_mul_f32 v[30:31], v[30:31], v[0:1] op_sel_hi:[1,0]
	v_pk_mul_f32 v[20:21], v[20:21], v[0:1] op_sel_hi:[1,0]
	v_pk_mul_f32 v[18:19], v[18:19], v[0:1] op_sel_hi:[1,0]
	v_pk_mul_f32 v[12:13], v[12:13], v[0:1] op_sel_hi:[1,0]
	v_pk_mul_f32 v[10:11], v[10:11], v[0:1] op_sel_hi:[1,0]
	s_waitcnt vmcnt(7) lgkmcnt(0)
	v_pk_add_f32 v[8:9], v[174:175], 1.0 op_sel_hi:[1, 0]
	v_pk_mul_f32 v[2:3], v[168:169], v[30:31]
	v_pk_mul_f32 v[4:5], v[170:171], v[32:33]
	v_pk_add_f32 v[6:7], v[172:173], 1.0 op_sel_hi:[1, 0]
	v_pk_fma_f32 v[4:5], v[8:9], v[4:5], v[178:179]
	v_pk_fma_f32 v[2:3], v[6:7], v[2:3], v[176:177]
	v_lshl_add_u64 v[6:7], v[38:39], 0, v[82:83]
	v_cvt_pk_bf16_f32 v2, v2, v3
	v_cvt_pk_bf16_f32 v3, v4, v5
	global_store_dwordx2 v[86:87], v[2:3], off offset:512
	s_waitcnt vmcnt(5) lgkmcnt(0)
	v_pk_add_f32 v[8:9], v[186:187], 1.0 op_sel_hi:[1, 0]
	v_pk_mul_f32 v[2:3], v[180:181], v[18:19]
	v_pk_mul_f32 v[4:5], v[182:183], v[20:21]
	v_pk_add_f32 v[6:7], v[184:185], 1.0 op_sel_hi:[1, 0]
	v_pk_fma_f32 v[4:5], v[8:9], v[4:5], v[190:191]
	v_pk_fma_f32 v[2:3], v[6:7], v[2:3], v[188:189]
	v_lshl_add_u64 v[6:7], v[38:39], 0, v[84:85]
	v_cvt_pk_bf16_f32 v2, v2, v3
	v_cvt_pk_bf16_f32 v3, v4, v5
	global_store_dwordx2 v[86:87], v[2:3], off offset:1024
	s_waitcnt vmcnt(3) lgkmcnt(0)
	v_pk_add_f32 v[8:9], v[198:199], 1.0 op_sel_hi:[1, 0]
	v_pk_mul_f32 v[2:3], v[10:11], v[192:193]
	v_pk_mul_f32 v[4:5], v[12:13], v[194:195]
	v_pk_add_f32 v[6:7], v[196:197], 1.0 op_sel_hi:[1, 0]
	v_pk_fma_f32 v[4:5], v[4:5], v[8:9], v[202:203]
	v_pk_fma_f32 v[2:3], v[2:3], v[6:7], v[200:201]
	s_nop 0
	v_cvt_pk_bf16_f32 v2, v2, v3
	v_cvt_pk_bf16_f32 v3, v4, v5
	global_store_dwordx2 v[86:87], v[2:3], off offset:1536
	s_or_b64 exec, exec, s[34:35]
	v_cmp_gt_i32_e32 vcc, s15, v88
	s_and_saveexec_b64 s[34:35], vcc
	s_cbranch_execnz .LBB0_566

.LBB0_566:
	v_min_i32_e32 v0, 0x8000, v88
	v_ashrrev_i32_e32 v0, 12, v0
	v_lshl_add_u32 v222, v0, 13, v223
	v_mul_i32_i24_e32 v2, 0x1800, v0
	v_ashrrev_i32_e32 v3, 31, v2
	v_lshl_add_u64 v[10:11], v[2:3], 2, s[44:45]
	v_lshl_add_u64 v[18:19], v[10:11], 0, s[8:9]
	v_mov_b32_e32 v79, v1
	v_lshl_add_u64 v[6:7], v[18:19], 0, v[78:79]
	ds_read_b128 v[2:5], v242
	v_lshl_add_u64 v[20:21], v[10:11], 0, v[78:79]
	ds_read_b128 v[6:9], v222 offset:4096
	v_mul_f32_e32 v0, v47, v47
	ds_read_b128 v[10:13], v222
	v_mov_b32_e32 v81, v1
	v_mov_b32_e32 v83, v1
	v_mov_b32_e32 v85, v1
	ds_read_b128 v[168:171], v242 offset:1024
	v_lshl_add_u64 v[172:173], v[18:19], 0, v[80:81]
	ds_read_b128 v[172:175], v222 offset:5120
	ds_read_b128 v[176:179], v222 offset:1024
	ds_read_b128 v[180:183], v242 offset:2048
	v_lshl_add_u64 v[184:185], v[18:19], 0, v[82:83]
	ds_read_b128 v[184:187], v222 offset:6144
	ds_read_b128 v[188:191], v222 offset:2048
	ds_read_b128 v[192:195], v242 offset:3072
	v_lshl_add_u64 v[196:197], v[18:19], 0, v[84:85]
	ds_read_b128 v[196:199], v222 offset:7168
	ds_read_b128 v[200:203], v222 offset:3072
	v_mul_f32_e32 v22, v43, v43
	v_mul_f32_e32 v23, v27, v27
	v_fmac_f32_e32 v0, v46, v46
	v_fmac_f32_e32 v22, v42, v42
	v_mul_f32_e32 v24, v15, v15
	v_fmac_f32_e32 v23, v26, v26
	v_fmac_f32_e32 v0, v48, v48
	v_fmac_f32_e32 v22, v44, v44
	v_fmac_f32_e32 v24, v14, v14
	v_fmac_f32_e32 v23, v28, v28
	v_fmac_f32_e32 v0, v49, v49
	v_fmac_f32_e32 v22, v45, v45
	v_fmac_f32_e32 v24, v16, v16
	v_fmac_f32_e32 v23, v29, v29
	v_add_f32_e32 v0, v22, v0
	v_fmac_f32_e32 v24, v17, v17
	v_add_f32_e32 v0, v23, v0
	v_add_f32_e32 v0, v24, v0
	ds_bpermute_b32 v22, v102, v0
	v_ashrrev_i32_e32 v89, 31, v88
	v_mov_b32_e32 v81, v1
	v_mov_b32_e32 v83, v1
	v_mov_b32_e32 v85, v1
	s_waitcnt lgkmcnt(0)
	v_add_f32_e32 v0, v0, v22
	ds_bpermute_b32 v22, v103, v0
	s_waitcnt lgkmcnt(0)
	v_add_f32_e32 v0, v0, v22
	ds_bpermute_b32 v22, v104, v0
	s_waitcnt lgkmcnt(0)
	v_add_f32_e32 v0, v0, v22
	ds_bpermute_b32 v22, v105, v0
	s_waitcnt lgkmcnt(0)
	v_add_f32_e32 v0, v0, v22
	ds_bpermute_b32 v22, v106, v0
	s_waitcnt lgkmcnt(0)
	v_add_f32_e32 v0, v0, v22
	ds_bpermute_b32 v22, v107, v0
	s_waitcnt lgkmcnt(0)
	v_add_f32_e32 v0, v0, v22
	v_fmamk_f32 v0, v0, 0x3a800000, v218
	v_mul_f32_e32 v22, 0x4b800000, v0
	v_cmp_gt_f32_e32 vcc, s13, v0
	s_waitcnt vmcnt(10) lgkmcnt(0)
	v_pk_add_f32 v[8:9], v[8:9], 1.0 op_sel_hi:[1,0]
	v_cndmask_b32_e32 v0, v0, v22, vcc
	v_rsq_f32_e32 v0, v0
	v_pk_add_f32 v[6:7], v[6:7], 1.0 op_sel_hi:[1,0]
	v_lshlrev_b64 v[22:23], 11, v[88:89]
	v_lshl_add_u64 v[22:23], v[74:75], 0, v[22:23]
	v_mul_f32_e32 v24, 0x45800000, v0
	v_cndmask_b32_e32 v0, v0, v24, vcc
	v_pk_mul_f32 v[24:25], v[48:49], v[0:1] op_sel_hi:[1,0]
	v_pk_mul_f32 v[30:31], v[46:47], v[0:1] op_sel_hi:[1,0]
	v_pk_mul_f32 v[4:5], v[4:5], v[24:25]
	v_pk_mul_f32 v[2:3], v[2:3], v[30:31]
	s_waitcnt vmcnt(9) lgkmcnt(0)
	v_pk_fma_f32 v[4:5], v[8:9], v[4:5], v[12:13]
	v_pk_fma_f32 v[2:3], v[6:7], v[2:3], v[10:11]
	v_lshl_add_u64 v[6:7], v[18:19], 0, v[80:81]
	v_cvt_pk_bf16_f32 v2, v2, v3
	v_cvt_pk_bf16_f32 v3, v4, v5
	global_store_dwordx2 v[22:23], v[2:3], off
	v_pk_mul_f32 v[24:25], v[44:45], v[0:1] op_sel_hi:[1,0]
	v_pk_mul_f32 v[30:31], v[42:43], v[0:1] op_sel_hi:[1,0]
	v_pk_mul_f32 v[26:27], v[26:27], v[0:1] op_sel_hi:[1,0]
	v_pk_mul_f32 v[16:17], v[16:17], v[0:1] op_sel_hi:[1,0]
	v_pk_mul_f32 v[14:15], v[14:15], v[0:1] op_sel_hi:[1,0]
	s_waitcnt vmcnt(7) lgkmcnt(0)
	v_pk_add_f32 v[8:9], v[174:175], 1.0 op_sel_hi:[1, 0]
	v_pk_mul_f32 v[2:3], v[168:169], v[30:31]
	v_pk_mul_f32 v[4:5], v[170:171], v[24:25]
	v_pk_add_f32 v[6:7], v[172:173], 1.0 op_sel_hi:[1, 0]
	v_pk_fma_f32 v[4:5], v[8:9], v[4:5], v[178:179]
	v_pk_fma_f32 v[2:3], v[6:7], v[2:3], v[176:177]
	v_lshl_add_u64 v[6:7], v[18:19], 0, v[82:83]
	v_cvt_pk_bf16_f32 v2, v2, v3
	v_cvt_pk_bf16_f32 v3, v4, v5
	global_store_dwordx2 v[22:23], v[2:3], off offset:512
	v_pk_mul_f32 v[24:25], v[28:29], v[0:1] op_sel_hi:[1,0]
	s_waitcnt vmcnt(5) lgkmcnt(0)
	v_pk_add_f32 v[8:9], v[186:187], 1.0 op_sel_hi:[1, 0]
	v_pk_mul_f32 v[2:3], v[180:181], v[26:27]
	v_pk_mul_f32 v[4:5], v[182:183], v[24:25]
	v_pk_add_f32 v[6:7], v[184:185], 1.0 op_sel_hi:[1, 0]
	v_pk_fma_f32 v[4:5], v[8:9], v[4:5], v[190:191]
	v_pk_fma_f32 v[2:3], v[6:7], v[2:3], v[188:189]
	v_lshl_add_u64 v[6:7], v[18:19], 0, v[84:85]
	v_cvt_pk_bf16_f32 v2, v2, v3
	v_cvt_pk_bf16_f32 v3, v4, v5
	global_store_dwordx2 v[22:23], v[2:3], off offset:1024
	s_waitcnt vmcnt(3) lgkmcnt(0)
	v_pk_add_f32 v[8:9], v[198:199], 1.0 op_sel_hi:[1, 0]
	v_pk_mul_f32 v[2:3], v[14:15], v[192:193]
	v_pk_mul_f32 v[4:5], v[16:17], v[194:195]
	v_pk_add_f32 v[6:7], v[196:197], 1.0 op_sel_hi:[1, 0]
	v_pk_fma_f32 v[4:5], v[4:5], v[8:9], v[202:203]
	v_pk_fma_f32 v[2:3], v[2:3], v[6:7], v[200:201]
	s_nop 0
	v_cvt_pk_bf16_f32 v2, v2, v3
	v_cvt_pk_bf16_f32 v3, v4, v5
	global_store_dwordx2 v[22:23], v[2:3], off offset:1536
	s_or_b64 exec, exec, s[34:35]
	v_cmp_gt_i32_e32 vcc, s15, v90
	s_and_saveexec_b64 s[34:35], vcc
	s_cbranch_execz .LBB0_529
.LBB0_567:
	v_min_i32_e32 v0, 0x8000, v90
	v_ashrrev_i32_e32 v0, 12, v0
	v_lshl_add_u32 v222, v0, 13, v223
	v_mul_i32_i24_e32 v2, 0x1800, v0
	v_ashrrev_i32_e32 v3, 31, v2
	v_lshl_add_u64 v[10:11], v[2:3], 2, s[44:45]
	v_lshl_add_u64 v[14:15], v[10:11], 0, s[8:9]
	v_mov_b32_e32 v79, v1
	v_lshl_add_u64 v[6:7], v[14:15], 0, v[78:79]
	ds_read_b128 v[2:5], v242
	v_lshl_add_u64 v[16:17], v[10:11], 0, v[78:79]
	ds_read_b128 v[6:9], v222 offset:4096
	v_mul_f32_e32 v0, v63, v63
	ds_read_b128 v[10:13], v222
	v_mov_b32_e32 v81, v1
	v_mov_b32_e32 v83, v1
	v_mov_b32_e32 v85, v1
	ds_read_b128 v[168:171], v242 offset:1024
	v_lshl_add_u64 v[172:173], v[14:15], 0, v[80:81]
	ds_read_b128 v[172:175], v222 offset:5120
	ds_read_b128 v[176:179], v222 offset:1024
	ds_read_b128 v[180:183], v242 offset:2048
	v_lshl_add_u64 v[184:185], v[14:15], 0, v[82:83]
	ds_read_b128 v[184:187], v222 offset:6144
	ds_read_b128 v[188:191], v222 offset:2048
	ds_read_b128 v[192:195], v242 offset:3072
	v_lshl_add_u64 v[196:197], v[14:15], 0, v[84:85]
	ds_read_b128 v[196:199], v222 offset:7168
	ds_read_b128 v[200:203], v222 offset:3072
	v_mul_f32_e32 v18, v59, v59
	v_mul_f32_e32 v19, v55, v55
	v_fmac_f32_e32 v0, v62, v62
	v_fmac_f32_e32 v18, v58, v58
	v_mul_f32_e32 v20, v51, v51
	v_fmac_f32_e32 v19, v54, v54
	v_fmac_f32_e32 v0, v64, v64
	v_fmac_f32_e32 v18, v60, v60
	v_fmac_f32_e32 v20, v50, v50
	v_fmac_f32_e32 v19, v56, v56
	v_fmac_f32_e32 v0, v65, v65
	v_fmac_f32_e32 v18, v61, v61
	v_fmac_f32_e32 v20, v52, v52
	v_fmac_f32_e32 v19, v57, v57
	v_add_f32_e32 v0, v18, v0
	v_fmac_f32_e32 v20, v53, v53
	v_add_f32_e32 v0, v19, v0
	v_add_f32_e32 v0, v20, v0
	ds_bpermute_b32 v18, v102, v0
	v_ashrrev_i32_e32 v91, 31, v90
	v_mov_b32_e32 v81, v1
	v_mov_b32_e32 v83, v1
	v_mov_b32_e32 v85, v1
	s_waitcnt lgkmcnt(0)
	v_add_f32_e32 v0, v0, v18
	ds_bpermute_b32 v18, v103, v0
	s_waitcnt lgkmcnt(0)
	v_add_f32_e32 v0, v0, v18
	ds_bpermute_b32 v18, v104, v0
	s_waitcnt lgkmcnt(0)
	v_add_f32_e32 v0, v0, v18
	ds_bpermute_b32 v18, v105, v0
	s_waitcnt lgkmcnt(0)
	v_add_f32_e32 v0, v0, v18
	ds_bpermute_b32 v18, v106, v0
	s_waitcnt lgkmcnt(0)
	v_add_f32_e32 v0, v0, v18
	ds_bpermute_b32 v18, v107, v0
	s_waitcnt lgkmcnt(0)
	v_add_f32_e32 v0, v0, v18
	v_fmamk_f32 v0, v0, 0x3a800000, v218
	v_mul_f32_e32 v18, 0x4b800000, v0
	v_cmp_gt_f32_e32 vcc, s13, v0
	s_waitcnt vmcnt(10) lgkmcnt(0)
	v_pk_add_f32 v[8:9], v[8:9], 1.0 op_sel_hi:[1,0]
	v_cndmask_b32_e32 v0, v0, v18, vcc
	v_rsq_f32_e32 v0, v0
	v_pk_add_f32 v[6:7], v[6:7], 1.0 op_sel_hi:[1,0]
	v_lshlrev_b64 v[18:19], 11, v[90:91]
	v_lshl_add_u64 v[18:19], v[74:75], 0, v[18:19]
	v_mul_f32_e32 v20, 0x45800000, v0
	v_cndmask_b32_e32 v0, v0, v20, vcc
	v_pk_mul_f32 v[20:21], v[64:65], v[0:1] op_sel_hi:[1,0]
	v_pk_mul_f32 v[22:23], v[62:63], v[0:1] op_sel_hi:[1,0]
	v_pk_mul_f32 v[4:5], v[4:5], v[20:21]
	v_pk_mul_f32 v[2:3], v[2:3], v[22:23]
	s_waitcnt vmcnt(9) lgkmcnt(0)
	v_pk_fma_f32 v[4:5], v[8:9], v[4:5], v[12:13]
	v_pk_fma_f32 v[2:3], v[6:7], v[2:3], v[10:11]
	v_lshl_add_u64 v[6:7], v[14:15], 0, v[80:81]
	v_cvt_pk_bf16_f32 v2, v2, v3
	v_cvt_pk_bf16_f32 v3, v4, v5
	global_store_dwordx2 v[18:19], v[2:3], off
	v_pk_mul_f32 v[20:21], v[60:61], v[0:1] op_sel_hi:[1,0]
	v_pk_mul_f32 v[22:23], v[58:59], v[0:1] op_sel_hi:[1,0]
	s_waitcnt vmcnt(7) lgkmcnt(0)
	v_pk_add_f32 v[8:9], v[174:175], 1.0 op_sel_hi:[1, 0]
	v_pk_mul_f32 v[2:3], v[168:169], v[22:23]
	v_pk_mul_f32 v[4:5], v[170:171], v[20:21]
	v_pk_add_f32 v[6:7], v[172:173], 1.0 op_sel_hi:[1, 0]
	v_pk_fma_f32 v[4:5], v[8:9], v[4:5], v[178:179]
	v_pk_fma_f32 v[2:3], v[6:7], v[2:3], v[176:177]
	v_lshl_add_u64 v[6:7], v[14:15], 0, v[82:83]
	v_cvt_pk_bf16_f32 v2, v2, v3
	v_cvt_pk_bf16_f32 v3, v4, v5
	global_store_dwordx2 v[18:19], v[2:3], off offset:512
	v_pk_mul_f32 v[20:21], v[56:57], v[0:1] op_sel_hi:[1,0]
	v_pk_mul_f32 v[22:23], v[54:55], v[0:1] op_sel_hi:[1,0]
	s_waitcnt vmcnt(5) lgkmcnt(0)
	v_pk_add_f32 v[8:9], v[186:187], 1.0 op_sel_hi:[1, 0]
	v_pk_mul_f32 v[2:3], v[180:181], v[22:23]
	v_pk_mul_f32 v[4:5], v[182:183], v[20:21]
	v_pk_add_f32 v[6:7], v[184:185], 1.0 op_sel_hi:[1, 0]
	v_pk_fma_f32 v[4:5], v[8:9], v[4:5], v[190:191]
	v_pk_fma_f32 v[2:3], v[6:7], v[2:3], v[188:189]
	v_lshl_add_u64 v[6:7], v[14:15], 0, v[84:85]
	v_cvt_pk_bf16_f32 v2, v2, v3
	v_cvt_pk_bf16_f32 v3, v4, v5
	global_store_dwordx2 v[18:19], v[2:3], off offset:1024
	v_pk_mul_f32 v[14:15], v[52:53], v[0:1] op_sel_hi:[1,0]
	v_pk_mul_f32 v[16:17], v[50:51], v[0:1] op_sel_hi:[1,0]
	s_waitcnt vmcnt(3) lgkmcnt(0)
	v_pk_add_f32 v[8:9], v[198:199], 1.0 op_sel_hi:[1, 0]
	v_pk_mul_f32 v[2:3], v[16:17], v[192:193]
	v_pk_mul_f32 v[4:5], v[14:15], v[194:195]
	v_pk_add_f32 v[6:7], v[196:197], 1.0 op_sel_hi:[1, 0]
	v_pk_fma_f32 v[4:5], v[4:5], v[8:9], v[202:203]
	v_pk_fma_f32 v[2:3], v[2:3], v[6:7], v[200:201]
	s_nop 0
	v_cvt_pk_bf16_f32 v2, v2, v3
	v_cvt_pk_bf16_f32 v3, v4, v5
	global_store_dwordx2 v[18:19], v[2:3], off offset:1536
	s_branch .LBB0_529
	s_nop 0
	s_nop 0
